# attention epilogue: the 8 gate loads issued together instead of load-wait-store 8 times
# baseline (speedup 1.0000x reference)
; __device__ __forceinline__ unsigned pk2(float lo, float hi) { const f32x2 v = {lo, hi}; return __builtin_bit_cast(unsigned, __builtin_convertvector(v, bf16v2)); }
; __device__ __forceinline__ void attn_phase(unsigned char* lds, const Params& p, int l, const int tid) {
;     ...
;         if (wave_active) {
;             const float inv = 1.f / l_i;
;             const size_t row = smp ? (size_t)(MP + b * 32 + qloc) : (size_t)(b * 4096 + cp * 128 + qloc);
; #pragma unroll
;             for (int n = 0; n < 8; ++n) { const int d = n * 16 + quad * 4;
;                 const u32x2 g2 = *(const u32x2*)(GB + row * 1024 + h * 128 + d);
;                 const float g0 = __uint_as_float(g2[0] << 16), g1 = __uint_as_float(g2[0] & 0xffff0000u), g2f = __uint_as_float(g2[1] << 16), g3 = __uint_as_float(g2[1] & 0xffff0000u);
;                 u32x2 pk; pk[0] = pk2(o[n][0] * inv * g0, o[n][1] * inv * g1); pk[1] = pk2(o[n][2] * inv * g2f, o[n][3] * inv * g3);
;                 *(u32x2*)(H + row * 2048 + 1024 + h * 128 + d) = pk; }
;         }
.LBB0_422:
	s_xor_b64 s[26:27], s[28:29], -1
	s_and_saveexec_b64 s[14:15], s[26:27]
	s_cbranch_execz .LBB0_424
	s_waitcnt vmcnt(3)
	v_div_scale_f32 v24, s[26:27], v156, v156, 1.0
	v_rcp_f32_e32 v25, v24
	s_lshl_b32 s26, s20, 5
	s_lshl_b32 s20, s20, 12
	s_add_i32 s26, s26, 0x8000
	v_fma_f32 v26, -v24, v25, 1.0
	v_fmac_f32_e32 v25, v26, v25
	v_div_scale_f32 v26, vcc, 1.0, v156, 1.0
	v_mul_f32_e32 v27, v26, v25
	s_add_i32 s20, s20, s21
	s_waitcnt vmcnt(2)
	v_fma_f32 v28, -v24, v27, v26
	s_and_b64 s[12:13], s[12:13], exec
	v_fmac_f32_e32 v27, v28, v25
	s_cselect_b32 s12, s26, s20
	v_fma_f32 v24, -v24, v27, v26
	v_add_u32_e32 v26, s12, v101
	v_div_fmas_f32 v24, v24, v25, v27
	v_ashrrev_i32_e32 v27, 31, v26
	v_lshlrev_b64 v[28:29], 11, v[26:27]
	v_lshl_add_u64 v[28:29], s[16:17], 0, v[28:29]
	s_lshl_b64 s[12:13], s[24:25], 1
	v_lshl_add_u64 v[28:29], v[28:29], 0, s[12:13]
	v_lshlrev_b32_e32 v136, 1, v102
	v_lshl_add_u64 v[28:29], v[28:29], 0, v[136:137]
	global_load_dwordx2 v[80:81], v[28:29], off
	global_load_dwordx2 v[82:83], v[28:29], off offset:32
	global_load_dwordx2 v[84:85], v[28:29], off offset:64
	global_load_dwordx2 v[86:87], v[28:29], off offset:96
	global_load_dwordx2 v[88:89], v[28:29], off offset:128
	global_load_dwordx2 v[90:91], v[28:29], off offset:160
	global_load_dwordx2 v[92:93], v[28:29], off offset:192
	global_load_dwordx2 v[94:95], v[28:29], off offset:224
	v_div_fixup_f32 v24, v24, v156, 1.0
	v_readlane_b32 s20, v246, 52
	v_readlane_b32 s21, v246, 53
	s_waitcnt vmcnt(9)
	v_lshlrev_b64 v[26:27], 12, v[26:27]
	v_pk_mul_f32 v[60:61], v[60:61], v[24:25] op_sel_hi:[1,0]
	v_pk_mul_f32 v[62:63], v[62:63], v[24:25] op_sel_hi:[1,0]
	v_pk_mul_f32 v[40:41], v[40:41], v[24:25] op_sel_hi:[1,0]
	v_pk_mul_f32 v[42:43], v[42:43], v[24:25] op_sel_hi:[1,0]
	v_pk_mul_f32 v[20:21], v[20:21], v[24:25] op_sel_hi:[1,0]
	v_pk_mul_f32 v[22:23], v[22:23], v[24:25] op_sel_hi:[1,0]
	v_pk_mul_f32 v[16:17], v[16:17], v[24:25] op_sel_hi:[1,0]
	v_pk_mul_f32 v[18:19], v[18:19], v[24:25] op_sel_hi:[1,0]
	v_pk_mul_f32 v[12:13], v[12:13], v[24:25] op_sel_hi:[1,0]
	v_pk_mul_f32 v[14:15], v[14:15], v[24:25] op_sel_hi:[1,0]
	v_pk_mul_f32 v[8:9], v[8:9], v[24:25] op_sel_hi:[1,0]
	v_pk_mul_f32 v[10:11], v[10:11], v[24:25] op_sel_hi:[1,0]
	v_pk_mul_f32 v[4:5], v[4:5], v[24:25] op_sel_hi:[1,0]
	v_pk_mul_f32 v[6:7], v[6:7], v[24:25] op_sel_hi:[1,0]
	v_pk_mul_f32 v[0:1], v[0:1], v[24:25] op_sel_hi:[1,0]
	v_pk_mul_f32 v[2:3], v[2:3], v[24:25] op_sel_hi:[1,0]
	v_lshl_add_u64 v[26:27], s[20:21], 0, v[26:27]
	v_lshl_add_u64 v[26:27], v[26:27], 0, s[12:13]
	s_mov_b64 s[12:13], 0x4100800
	v_lshl_add_u64 v[32:33], v[26:27], 0, v[136:137]
	v_lshl_add_u64 v[26:27], v[32:33], 0, s[12:13]
	s_waitcnt vmcnt(0)
	v_lshlrev_b32_e32 v32, 16, v80
	v_and_b32_e32 v33, 0xffff0000, v80
	v_lshlrev_b32_e32 v34, 16, v81
	v_and_b32_e32 v35, 0xffff0000, v81
	v_pk_mul_f32 v[60:61], v[60:61], v[32:33]
	v_pk_mul_f32 v[62:63], v[62:63], v[34:35]
	v_cvt_pk_bf16_f32 v80, v60, v61
	v_cvt_pk_bf16_f32 v81, v62, v63
	global_store_dwordx2 v[26:27], v[80:81], off
	v_lshlrev_b32_e32 v32, 16, v82
	v_and_b32_e32 v33, 0xffff0000, v82
	v_lshlrev_b32_e32 v34, 16, v83
	v_and_b32_e32 v35, 0xffff0000, v83
	v_pk_mul_f32 v[40:41], v[40:41], v[32:33]
	v_pk_mul_f32 v[42:43], v[42:43], v[34:35]
	v_cvt_pk_bf16_f32 v82, v40, v41
	v_cvt_pk_bf16_f32 v83, v42, v43
	global_store_dwordx2 v[26:27], v[82:83], off offset:32
	v_lshlrev_b32_e32 v32, 16, v84
	v_and_b32_e32 v33, 0xffff0000, v84
	v_lshlrev_b32_e32 v34, 16, v85
	v_and_b32_e32 v35, 0xffff0000, v85
	v_pk_mul_f32 v[20:21], v[20:21], v[32:33]
	v_pk_mul_f32 v[22:23], v[22:23], v[34:35]
	v_cvt_pk_bf16_f32 v84, v20, v21
	v_cvt_pk_bf16_f32 v85, v22, v23
	global_store_dwordx2 v[26:27], v[84:85], off offset:64
	v_lshlrev_b32_e32 v32, 16, v86
	v_and_b32_e32 v33, 0xffff0000, v86
	v_lshlrev_b32_e32 v34, 16, v87
	v_and_b32_e32 v35, 0xffff0000, v87
	v_pk_mul_f32 v[16:17], v[16:17], v[32:33]
	v_pk_mul_f32 v[18:19], v[18:19], v[34:35]
	v_cvt_pk_bf16_f32 v86, v16, v17
	v_cvt_pk_bf16_f32 v87, v18, v19
	global_store_dwordx2 v[26:27], v[86:87], off offset:96
	v_lshlrev_b32_e32 v32, 16, v88
	v_and_b32_e32 v33, 0xffff0000, v88
	v_lshlrev_b32_e32 v34, 16, v89
	v_and_b32_e32 v35, 0xffff0000, v89
	v_pk_mul_f32 v[12:13], v[12:13], v[32:33]
	v_pk_mul_f32 v[14:15], v[14:15], v[34:35]
	v_cvt_pk_bf16_f32 v88, v12, v13
	v_cvt_pk_bf16_f32 v89, v14, v15
	global_store_dwordx2 v[26:27], v[88:89], off offset:128
	v_lshlrev_b32_e32 v32, 16, v90
	v_and_b32_e32 v33, 0xffff0000, v90
	v_lshlrev_b32_e32 v34, 16, v91
	v_and_b32_e32 v35, 0xffff0000, v91
	v_pk_mul_f32 v[8:9], v[8:9], v[32:33]
	v_pk_mul_f32 v[10:11], v[10:11], v[34:35]
	v_cvt_pk_bf16_f32 v90, v8, v9
	v_cvt_pk_bf16_f32 v91, v10, v11
	global_store_dwordx2 v[26:27], v[90:91], off offset:160
	v_lshlrev_b32_e32 v32, 16, v92
	v_and_b32_e32 v33, 0xffff0000, v92
	v_lshlrev_b32_e32 v34, 16, v93
	v_and_b32_e32 v35, 0xffff0000, v93
	v_pk_mul_f32 v[4:5], v[4:5], v[32:33]
	v_pk_mul_f32 v[6:7], v[6:7], v[34:35]
	v_cvt_pk_bf16_f32 v92, v4, v5
	v_cvt_pk_bf16_f32 v93, v6, v7
	global_store_dwordx2 v[26:27], v[92:93], off offset:192
	v_lshlrev_b32_e32 v32, 16, v94
	v_and_b32_e32 v33, 0xffff0000, v94
	v_lshlrev_b32_e32 v34, 16, v95
	v_and_b32_e32 v35, 0xffff0000, v95
	v_pk_mul_f32 v[0:1], v[0:1], v[32:33]
	v_pk_mul_f32 v[2:3], v[2:3], v[34:35]
	v_cvt_pk_bf16_f32 v94, v0, v1
	v_cvt_pk_bf16_f32 v95, v2, v3
	global_store_dwordx2 v[26:27], v[94:95], off offset:224
